# selection phase 1: lane suffix sum via DPP inclusive scan instead of six ds_bpermute round trips
# baseline (speedup 1.0000x reference)
.LBB0_439:
	s_add_i32 s36, s81, 1
	s_lshr_b32 s36, s36, 1
	v_mov_b32_e32 v0, s81
	v_mov_b32_e32 v1, s36
	s_lshl_b32 s36, s36, 2
	v_or_b32_e32 v160, s38, v185
	v_cndmask_b32_e64 v0, v0, v1, s[40:41]
	v_mov_b32_e32 v1, s36
	v_cmp_lt_i32_e32 vcc, s16, v160
	v_mov_b32_e32 v3, 0
	v_cndmask_b32_e64 v5, v1, 0, s[40:41]
	v_lshlrev_b32_e32 v6, 2, v0
	s_mov_b64 s[42:43], -1
	v_lshlrev_b32_e32 v162, 2, v172
	v_mov_b32_e32 v4, 0
	s_waitcnt lgkmcnt(0)
	s_barrier
	v_readlane_b32 s100, v250, 48
	v_readlane_b32 s101, v250, 49
	v_and_b32_e32 v243, 15, v172
	v_lshrrev_b32_e32 v244, 4, v172
	v_lshlrev_b32_e32 v243, 9, v243
	v_lshl_add_u32 v243, v244, 4, v243
	v_lshl_add_u32 v243, v160, 13, v243
	s_nop 1
	global_load_dwordx4 v[64:67], v243, s[100:101]
	global_load_dwordx4 v[68:71], v243, s[100:101] offset:64
	global_load_dwordx4 v[72:75], v243, s[100:101] offset:128
	global_load_dwordx4 v[76:79], v243, s[100:101] offset:192
	global_load_dwordx4 v[80:83], v243, s[100:101] offset:256
	global_load_dwordx4 v[84:87], v243, s[100:101] offset:320
	global_load_dwordx4 v[88:91], v243, s[100:101] offset:384
	global_load_dwordx4 v[92:95], v243, s[100:101] offset:448
	s_and_saveexec_b64 s[38:39], vcc
	s_cbranch_execz .LBB0_441
	v_lshl_add_u32 v0, v172, 6, v187
	ds_read_b128 v[8:11], v0
	ds_read_b128 v[12:15], v0 offset:16
	s_waitcnt vmcnt(31)
	ds_read_b128 v[16:19], v0 offset:32
	s_waitcnt vmcnt(30)
	ds_read_b128 v[20:23], v0 offset:48
	s_waitcnt vmcnt(10)
	v_add_u32_e32 v35, 4, v162
	s_waitcnt lgkmcnt(3)
	v_add_u32_sdwa v0, v8, v8 dst_sel:DWORD dst_unused:UNUSED_PAD src0_sel:WORD_1 src1_sel:WORD_0
	v_and_b32_e32 v1, 0xffff, v9
	v_lshrrev_b32_e32 v2, 16, v9
	v_add3_u32 v0, v2, v0, v1
	v_and_b32_e32 v4, 0xffff, v10
	v_lshrrev_b32_e32 v7, 16, v10
	v_add3_u32 v0, v7, v0, v4
	v_and_b32_e32 v9, 0xffff, v11
	v_lshrrev_b32_e32 v10, 16, v11
	v_add3_u32 v0, v10, v0, v9
	s_waitcnt lgkmcnt(2)
	v_and_b32_e32 v11, 0xffff, v12
	v_lshrrev_b32_e32 v12, 16, v12
	v_add3_u32 v0, v12, v0, v11
	v_and_b32_e32 v24, 0xffff, v13
	v_lshrrev_b32_e32 v13, 16, v13
	v_add3_u32 v0, v13, v0, v24
	v_and_b32_e32 v25, 0xffff, v14
	v_lshrrev_b32_e32 v14, 16, v14
	v_add3_u32 v0, v14, v0, v25
	v_and_b32_e32 v26, 0xffff, v15
	v_lshrrev_b32_e32 v15, 16, v15
	v_add3_u32 v0, v15, v0, v26
	s_waitcnt lgkmcnt(1)
	v_and_b32_e32 v27, 0xffff, v16
	v_lshrrev_b32_e32 v16, 16, v16
	v_add3_u32 v0, v16, v0, v27
	v_and_b32_e32 v28, 0xffff, v17
	v_lshrrev_b32_e32 v17, 16, v17
	v_add3_u32 v0, v17, v0, v28
	v_and_b32_e32 v29, 0xffff, v18
	v_lshrrev_b32_e32 v18, 16, v18
	v_add3_u32 v0, v18, v0, v29
	v_and_b32_e32 v30, 0xffff, v19
	v_lshrrev_b32_e32 v19, 16, v19
	v_add3_u32 v0, v19, v0, v30
	s_waitcnt lgkmcnt(0)
	v_and_b32_e32 v31, 0xffff, v20
	v_lshrrev_b32_e32 v20, 16, v20
	v_add3_u32 v0, v20, v0, v31
	v_and_b32_e32 v32, 0xffff, v21
	v_lshrrev_b32_e32 v21, 16, v21
	v_add3_u32 v0, v21, v0, v32
	v_and_b32_e32 v33, 0xffff, v22
	v_lshrrev_b32_e32 v22, 16, v22
	v_add3_u32 v0, v22, v0, v33
	v_and_b32_e32 v34, 0xffff, v23
	v_lshrrev_b32_e32 v23, 16, v23
	v_add3_u32 v0, v23, v0, v34
	s_movk_i32 s16, 0x100
	s_movk_i32 s15, 0xff
	v_cmp_ge_u32_e64 s[44:45], v5, v6
	v_mov_b32_e32 v36, v0
	s_nop 1
	v_add_u32_dpp v36, v36, v36 row_shr:1 row_mask:0xf bank_mask:0xf
	s_nop 1
	v_add_u32_dpp v36, v36, v36 row_shr:2 row_mask:0xf bank_mask:0xf
	s_nop 1
	v_add_u32_dpp v36, v36, v36 row_shr:4 row_mask:0xf bank_mask:0xf
	s_nop 1
	v_add_u32_dpp v36, v36, v36 row_shr:8 row_mask:0xf bank_mask:0xf
	s_nop 1
	v_add_u32_dpp v36, v36, v36 row_bcast:15 row_mask:0xa bank_mask:0xf
	s_nop 1
	v_add_u32_dpp v36, v36, v36 row_bcast:31 row_mask:0xc bank_mask:0xf
	s_nop 1
	v_readlane_b32 s36, v36, 63
	s_nop 1
	v_sub_u32_e32 v35, s36, v36
	v_add_u32_e32 v35, v35, v0
	v_sub_u32_e32 v0, v35, v0
	v_add_u32_e32 v0, v23, v0
	v_cmp_lt_i32_e64 s[46:47], s15, v35
	v_add_u32_e32 v23, v34, v0
	s_bcnt1_i32_b64 s42, s[46:47]
	v_cmp_lt_i32_e64 s[46:47], s15, v23
	v_add_u32_e32 v22, v22, v23
	s_add_i32 s42, s42, -1
	v_cndmask_b32_e64 v34, -1, 30, s[46:47]
	v_cmp_gt_i32_e64 s[46:47], s16, v0
	s_movk_i32 s16, 0xff
	s_nop 0
	v_cndmask_b32_e64 v0, 31, v34, s[46:47]
	v_cmp_lt_i32_e64 s[46:47], s15, v22
	v_cmp_gt_i32_e64 s[48:49], 0, v0
	s_and_b64 s[36:37], s[46:47], s[48:49]
	v_cndmask_b32_e64 v0, v0, 29, s[36:37]
	v_add_u32_e32 v22, v33, v22
	v_cmp_lt_i32_e64 s[46:47], s15, v22
	v_cmp_gt_i32_e64 s[48:49], 0, v0
	s_and_b64 s[36:37], s[46:47], s[48:49]
	v_cndmask_b32_e64 v0, v0, 28, s[36:37]
	v_add_u32_e32 v21, v21, v22
	v_cmp_lt_i32_e64 s[46:47], s15, v21
	v_cmp_gt_i32_e64 s[48:49], 0, v0
	s_and_b64 s[36:37], s[46:47], s[48:49]
	v_cndmask_b32_e64 v0, v0, 27, s[36:37]
	v_add_u32_e32 v21, v32, v21
	v_cmp_lt_i32_e64 s[46:47], s15, v21
	v_cmp_gt_i32_e64 s[48:49], 0, v0
	s_and_b64 s[36:37], s[46:47], s[48:49]
	v_cndmask_b32_e64 v0, v0, 26, s[36:37]
	v_add_u32_e32 v20, v20, v21
	v_cmp_lt_i32_e64 s[46:47], s15, v20
	v_cmp_gt_i32_e64 s[48:49], 0, v0
	s_and_b64 s[36:37], s[46:47], s[48:49]
	v_cndmask_b32_e64 v0, v0, 25, s[36:37]
	v_add_u32_e32 v20, v31, v20
	v_cmp_lt_i32_e64 s[46:47], s15, v20
	v_cmp_gt_i32_e64 s[48:49], 0, v0
	s_and_b64 s[36:37], s[46:47], s[48:49]
	v_cndmask_b32_e64 v0, v0, 24, s[36:37]
	v_add_u32_e32 v19, v19, v20
	v_cmp_lt_i32_e64 s[46:47], s15, v19
	v_cmp_gt_i32_e64 s[48:49], 0, v0
	s_and_b64 s[36:37], s[46:47], s[48:49]
	v_cndmask_b32_e64 v0, v0, 23, s[36:37]
	v_add_u32_e32 v19, v30, v19
	v_cmp_lt_i32_e64 s[46:47], s15, v19
	v_cmp_gt_i32_e64 s[48:49], 0, v0
	s_and_b64 s[36:37], s[46:47], s[48:49]
	v_cndmask_b32_e64 v0, v0, 22, s[36:37]
	v_add_u32_e32 v18, v18, v19
	v_cmp_lt_i32_e64 s[46:47], s15, v18
	v_cmp_gt_i32_e64 s[48:49], 0, v0
	s_and_b64 s[36:37], s[46:47], s[48:49]
	v_cndmask_b32_e64 v0, v0, 21, s[36:37]
	v_add_u32_e32 v18, v29, v18
	v_cmp_lt_i32_e64 s[46:47], s15, v18
	v_cmp_gt_i32_e64 s[48:49], 0, v0
	s_and_b64 s[36:37], s[46:47], s[48:49]
	v_cndmask_b32_e64 v0, v0, 20, s[36:37]
	v_add_u32_e32 v17, v17, v18
	v_cmp_lt_i32_e64 s[46:47], s15, v17
	v_cmp_gt_i32_e64 s[48:49], 0, v0
	s_and_b64 s[36:37], s[46:47], s[48:49]
	v_cndmask_b32_e64 v0, v0, 19, s[36:37]
	v_add_u32_e32 v17, v28, v17
	v_cmp_lt_i32_e64 s[46:47], s15, v17
	v_cmp_gt_i32_e64 s[48:49], 0, v0
	s_and_b64 s[36:37], s[46:47], s[48:49]
	v_cndmask_b32_e64 v0, v0, 18, s[36:37]
	v_add_u32_e32 v16, v16, v17
	v_cmp_lt_i32_e64 s[46:47], s15, v16
	v_cmp_gt_i32_e64 s[48:49], 0, v0
	s_and_b64 s[36:37], s[46:47], s[48:49]
	v_cndmask_b32_e64 v0, v0, 17, s[36:37]
	v_add_u32_e32 v16, v27, v16
	v_cmp_lt_i32_e64 s[46:47], s15, v16
	v_cmp_gt_i32_e64 s[48:49], 0, v0
	s_and_b64 s[36:37], s[46:47], s[48:49]
	v_cndmask_b32_e64 v0, v0, 16, s[36:37]
	v_add_u32_e32 v15, v15, v16
	v_cmp_lt_i32_e64 s[46:47], s15, v15
	v_cmp_gt_i32_e64 s[48:49], 0, v0
	s_and_b64 s[36:37], s[46:47], s[48:49]
	v_cndmask_b32_e64 v0, v0, 15, s[36:37]
	v_add_u32_e32 v15, v26, v15
	v_cmp_lt_i32_e64 s[46:47], s15, v15
	v_cmp_gt_i32_e64 s[48:49], 0, v0
	s_and_b64 s[36:37], s[46:47], s[48:49]
	v_cndmask_b32_e64 v0, v0, 14, s[36:37]
	v_add_u32_e32 v14, v14, v15
	v_cmp_lt_i32_e64 s[46:47], s15, v14
	v_cmp_gt_i32_e64 s[48:49], 0, v0
	s_and_b64 s[36:37], s[46:47], s[48:49]
	v_cndmask_b32_e64 v0, v0, 13, s[36:37]
	v_add_u32_e32 v14, v25, v14
	v_cmp_lt_i32_e64 s[46:47], s15, v14
	v_cmp_gt_i32_e64 s[48:49], 0, v0
	s_and_b64 s[36:37], s[46:47], s[48:49]
	v_cndmask_b32_e64 v0, v0, 12, s[36:37]
	v_add_u32_e32 v13, v13, v14
	v_cmp_lt_i32_e64 s[46:47], s15, v13
	v_cmp_gt_i32_e64 s[48:49], 0, v0
	s_and_b64 s[36:37], s[46:47], s[48:49]
	v_cndmask_b32_e64 v0, v0, 11, s[36:37]
	v_add_u32_e32 v13, v24, v13
	v_cmp_lt_i32_e64 s[46:47], s15, v13
	v_cmp_gt_i32_e64 s[48:49], 0, v0
	s_and_b64 s[36:37], s[46:47], s[48:49]
	v_cndmask_b32_e64 v0, v0, 10, s[36:37]
	v_add_u32_e32 v12, v12, v13
	v_cmp_lt_i32_e64 s[46:47], s15, v12
	v_cmp_gt_i32_e64 s[48:49], 0, v0
	s_and_b64 s[36:37], s[46:47], s[48:49]
	v_cndmask_b32_e64 v0, v0, 9, s[36:37]
	v_add_u32_e32 v11, v11, v12
	v_cmp_lt_i32_e64 s[46:47], s15, v11
	v_cmp_gt_i32_e64 s[48:49], 0, v0
	s_and_b64 s[36:37], s[46:47], s[48:49]
	v_cndmask_b32_e64 v0, v0, 8, s[36:37]
	v_add_u32_e32 v10, v10, v11
	v_cmp_lt_i32_e64 s[46:47], s15, v10
	v_cmp_gt_i32_e64 s[48:49], 0, v0
	s_and_b64 s[36:37], s[46:47], s[48:49]
	v_cndmask_b32_e64 v0, v0, 7, s[36:37]
	v_add_u32_e32 v9, v9, v10
	v_cmp_lt_i32_e64 s[46:47], s15, v9
	v_cmp_gt_i32_e64 s[48:49], 0, v0
	s_and_b64 s[36:37], s[46:47], s[48:49]
	v_cndmask_b32_e64 v0, v0, 6, s[36:37]
	v_add_u32_e32 v7, v7, v9
	v_cmp_lt_i32_e64 s[46:47], s15, v7
	v_cmp_gt_i32_e64 s[48:49], 0, v0
	s_and_b64 s[36:37], s[46:47], s[48:49]
	v_cndmask_b32_e64 v0, v0, 5, s[36:37]
	v_add_u32_e32 v4, v4, v7
	v_cmp_lt_i32_e64 s[46:47], s15, v4
	v_cmp_gt_i32_e64 s[48:49], 0, v0
	s_and_b64 s[36:37], s[46:47], s[48:49]
	v_cndmask_b32_e64 v0, v0, 4, s[36:37]
	v_add_u32_e32 v2, v2, v4
	v_cmp_lt_i32_e64 s[46:47], s15, v2
	v_cmp_gt_i32_e64 s[48:49], 0, v0
	s_and_b64 s[36:37], s[46:47], s[48:49]
	v_cndmask_b32_e64 v0, v0, 3, s[36:37]
	v_add_u32_e32 v1, v1, v2
	v_cmp_lt_i32_e64 s[46:47], s15, v1
	v_cmp_gt_i32_e64 s[48:49], 0, v0
	s_and_b64 s[36:37], s[46:47], s[48:49]
	v_cndmask_b32_e64 v0, v0, 2, s[36:37]
	v_add_u32_sdwa v1, v8, v1 dst_sel:DWORD dst_unused:UNUSED_PAD src0_sel:WORD_1 src1_sel:DWORD
	v_cmp_lt_i32_e64 s[46:47], s15, v1
	v_cmp_gt_i32_e64 s[48:49], 0, v0
	s_and_b64 s[36:37], s[46:47], s[48:49]
	v_cndmask_b32_e64 v0, v0, 1, s[36:37]
	v_add_u32_sdwa v1, v8, v1 dst_sel:DWORD dst_unused:UNUSED_PAD src0_sel:WORD_0 src1_sel:DWORD
	v_max_i32_e32 v2, 0, v0
	v_cmp_lt_i32_e64 s[46:47], s15, v1
	s_lshl_b32 s37, s42, 26
	s_nop 0
	v_cndmask_b32_e64 v0, v0, v2, s[46:47]
	s_nop 0
	v_readlane_b32 s36, v0, s42
	s_lshl_b32 s36, s36, 21
	s_add_i32 s36, s36, s37
	v_mov_b32_e32 v4, s36
	s_orn2_b64 s[42:43], s[44:45], exec
